# small deferred set: only layer-0 OUT/PG/PE conversions (4352 items) moved from the prologue to attention-phase idle waves
# baseline (speedup 1.0000x reference)
; __device__ __forceinline__ void prologue(ArgsP a, const Ctx& c) {
;     ...
;     constexpr int N_MID = DEFER_PG0 - DEFER_LO, N_PRO = PER_LAYER + N_MID + (PER_LAYER - DEFER_PG1);
;     for (int j = c.gw; j < N_PRO; j += c.NGW) {
;         const int it = j < PER_LAYER ? j : (j < PER_LAYER + N_MID ? PER_LAYER + DEFER_LO + (j - PER_LAYER) : PER_LAYER + DEFER_PG1 + (j - PER_LAYER - N_MID));
;         convert_item(a, c, it, scr);
.LBB0_542:
	s_cmp_lg_u32 s32, 0
	s_cselect_b32 s3, 1, 0
	s_lshr_b32 s3, s62, s3
	s_add_i32 s14, s14, s3
	s_mov_b32 s2, 0xacff
	s_cmp_lg_u32 s32, 0
	s_cselect_b32 s2, 0x10ff, s2
	s_cmp_gt_i32 s14, s2
	s_cbranch_scc1 .Lconv_exit
.LBB0_543:
	s_cmp_lg_u32 s32, 0
	s_cbranch_scc1 .Lmap_def
	s_mov_b32 s10, s14
	s_cmp_lt_i32 s14, 0x9c00
	s_cbranch_scc1 .LBB0_548
	s_add_i32 s10, s14, 0xa500
	s_cmp_lt_i32 s14, 0xac00
	s_cbranch_scc1 .LBB0_548
	s_add_i32 s10, s14, 0xad00
	s_branch .LBB0_548
.Lmap_def:
	s_add_i32 s10, s14, 0x9c00
